# gate/up tile loop: removed compiler loop-preheader vmcnt(0) before each tile's K loop (waited for previous epilogue stores + bias DMA)
# baseline (speedup 1.0000x reference)
; template <bool GATHER, bool FP8, class Epi, class Sched>
; __device__ __forceinline__ void gemm_phase(LAS unsigned char* lds, const int tid, const int K, const Sched& S, const Epi& E) {
;     ...
; #pragma unroll
;         for (int a = 0; a < 2; ++a)
; #pragma unroll
;             for (int b = 0; b < 2; ++b)
; #pragma unroll
;                 for (int m = 0; m < 4; ++m)
; #pragma unroll
;                     for (int n = 0; n < 2; ++n) acc[a][b][m][n] = (f32x4){zf, zf, zf, zf};
;         cur = nxt; cA = nA; cB = nB; ++ui;
.LBB0_93:
	s_ashr_i32 s51, s50, 31
	s_lshl_b64 s[16:17], s[50:51], 21
	v_readlane_b32 s12, v254, 55
	s_add_u32 s12, s12, s16
	v_readlane_b32 s16, v254, 56
	s_addc_u32 s20, s16, s17
	s_ashr_i32 s41, s40, 31
	s_lshl_b64 s[16:17], s[40:41], 18
	s_add_u32 s52, s12, s16
	s_addc_u32 s53, s20, s17
	s_and_b64 s[16:17], s[44:45], exec
	s_cselect_b32 s41, s53, s23
	s_cselect_b32 s51, s52, s22
	s_lshl_b32 s16, s73, 9
	s_add_u32 s17, s22, 0x10000
	v_readlane_b32 s20, v251, 39
	v_mov_b32_e32 v178, v188
	v_mov_b32_e32 v179, v33
	v_mov_b32_e32 v180, v190
	v_mov_b32_e32 v181, v33
	s_addc_u32 s12, s23, 0
	s_mov_b32 s71, -2
	v_readlane_b32 s21, v251, 40
	v_mov_b32_e32 v34, v186
	v_mov_b32_e32 v35, v186
	v_mov_b32_e32 v36, v186
	v_mov_b32_e32 v37, v186
	v_mov_b32_e32 v40, v186
	v_mov_b32_e32 v41, v186
	v_mov_b32_e32 v42, v186
	v_mov_b32_e32 v43, v186
	v_mov_b32_e32 v52, v186
	v_mov_b32_e32 v53, v186
	v_mov_b32_e32 v54, v186
	v_mov_b32_e32 v55, v186
	v_mov_b32_e32 v56, v186
	v_mov_b32_e32 v57, v186
	v_mov_b32_e32 v58, v186
	v_mov_b32_e32 v59, v186
	v_mov_b32_e32 v68, v186
	v_mov_b32_e32 v69, v186
	v_mov_b32_e32 v70, v186
	v_mov_b32_e32 v71, v186
	v_mov_b32_e32 v72, v186
	v_mov_b32_e32 v73, v186
	v_mov_b32_e32 v74, v186
	v_mov_b32_e32 v75, v186
	v_mov_b32_e32 v84, v186
	v_mov_b32_e32 v85, v186
	v_mov_b32_e32 v86, v186
	v_mov_b32_e32 v87, v186
	v_mov_b32_e32 v88, v186
	v_mov_b32_e32 v89, v186
	v_mov_b32_e32 v90, v186
	v_mov_b32_e32 v91, v186
	v_mov_b32_e32 v44, v186
	v_mov_b32_e32 v45, v186
	v_mov_b32_e32 v46, v186
	v_mov_b32_e32 v47, v186
	v_mov_b32_e32 v48, v186
	v_mov_b32_e32 v49, v186
	v_mov_b32_e32 v50, v186
	v_mov_b32_e32 v51, v186
	v_mov_b32_e32 v60, v186
	v_mov_b32_e32 v61, v186
	v_mov_b32_e32 v62, v186
	v_mov_b32_e32 v63, v186
	v_mov_b32_e32 v64, v186
	v_mov_b32_e32 v65, v186
	v_mov_b32_e32 v66, v186
	v_mov_b32_e32 v67, v186
	v_mov_b32_e32 v76, v186
	v_mov_b32_e32 v77, v186
	v_mov_b32_e32 v78, v186
	v_mov_b32_e32 v79, v186
	v_mov_b32_e32 v80, v186
	v_mov_b32_e32 v81, v186
	v_mov_b32_e32 v82, v186
	v_mov_b32_e32 v83, v186
	v_mov_b32_e32 v92, v186
	v_mov_b32_e32 v93, v186
	v_mov_b32_e32 v94, v186
	v_mov_b32_e32 v95, v186
	v_mov_b32_e32 v96, v186
	v_mov_b32_e32 v97, v186
	v_mov_b32_e32 v98, v186
	v_mov_b32_e32 v99, v186
	v_mov_b32_e32 v100, v186
	v_mov_b32_e32 v101, v186
	v_mov_b32_e32 v102, v186
	v_mov_b32_e32 v103, v186
	v_mov_b32_e32 v104, v186
	v_mov_b32_e32 v105, v186
	v_mov_b32_e32 v106, v186
	v_mov_b32_e32 v107, v186
	v_mov_b32_e32 v116, v186
	v_mov_b32_e32 v117, v186
	v_mov_b32_e32 v118, v186
	v_mov_b32_e32 v119, v186
	v_mov_b32_e32 v120, v186
	v_mov_b32_e32 v121, v186
	v_mov_b32_e32 v122, v186
	v_mov_b32_e32 v123, v186
	v_mov_b32_e32 v132, v186
	v_mov_b32_e32 v133, v186
	v_mov_b32_e32 v134, v186
	v_mov_b32_e32 v135, v186
	v_mov_b32_e32 v136, v186
	v_mov_b32_e32 v137, v186
	v_mov_b32_e32 v138, v186
	v_mov_b32_e32 v139, v186
	v_mov_b32_e32 v148, v186
	v_mov_b32_e32 v149, v186
	v_mov_b32_e32 v150, v186
	v_mov_b32_e32 v151, v186
	v_mov_b32_e32 v152, v186
	v_mov_b32_e32 v153, v186
	v_mov_b32_e32 v154, v186
	v_mov_b32_e32 v155, v186
	v_mov_b32_e32 v108, v186
	v_mov_b32_e32 v109, v186
	v_mov_b32_e32 v110, v186
	v_mov_b32_e32 v111, v186
	v_mov_b32_e32 v112, v186
	v_mov_b32_e32 v113, v186
	v_mov_b32_e32 v114, v186
	v_mov_b32_e32 v115, v186
	v_mov_b32_e32 v124, v186
	v_mov_b32_e32 v125, v186
	v_mov_b32_e32 v126, v186
	v_mov_b32_e32 v127, v186
	v_mov_b32_e32 v128, v186
	v_mov_b32_e32 v129, v186
	v_mov_b32_e32 v130, v186
	v_mov_b32_e32 v131, v186
	v_mov_b32_e32 v140, v186
	v_mov_b32_e32 v141, v186
	v_mov_b32_e32 v142, v186
	v_mov_b32_e32 v143, v186
	v_mov_b32_e32 v144, v186
	v_mov_b32_e32 v145, v186
	v_mov_b32_e32 v146, v186
	v_mov_b32_e32 v147, v186
	v_mov_b32_e32 v156, v186
	v_mov_b32_e32 v157, v186
	v_mov_b32_e32 v158, v186
	v_mov_b32_e32 v159, v186
	v_mov_b32_e32 v160, v186
	v_mov_b32_e32 v161, v186
	v_mov_b32_e32 v162, v186
	v_mov_b32_e32 v163, v186
	s_branch .LBB0_95
